# FoX and SWA unit epilogues: the 8 gate loads issued together, counted vmcnt per group
# speedup vs baseline: 1.0143x; 1.0044x over previous
; DI unsigned pack2(float a, float b) { f32x2 v = {a, b}; bf16x2_t r = __builtin_convertvector(v, bf16x2_t); return __builtin_bit_cast(unsigned, r); }
; DI float bflo(unsigned v) { return __uint_as_float(v << 16); }
; DI float bfhi(unsigned v) { return __uint_as_float(v & 0xffff0000u); }
; DI int otid() { int t = threadIdx.x; asm volatile("" : "+v"(t)); return t; }
; DI size_t blk(size_t row, int k, int R) { return ((size_t)(k >> 5) * R + row) * 32 + (k & 31); }
; DI float silu_f(float x) { return x / (1.f + __expf(-x)); }
; DI void store_gated(const f32x16 (&o)[2], float inv, bf16_t* G, size_t tok, int head) {
;   const int h = (otid() & 63) >> 5;
; #pragma unroll
;   for (int dt = 0; dt < 2; ++dt)
; #pragma unroll
;     for (int g = 0; g < 4; ++g) {
;       bf16_t* q = G + blk(tok, head * 64 + 32 * dt + 8 * g + 4 * h, NTOK);
;       const u32x2 gv = *(const u32x2*)q;
;       const float a0 = o[dt][4 * g] * inv * silu_f(bflo(gv[0])), a1 = o[dt][4 * g + 1] * inv * silu_f(bfhi(gv[0]));
;       const float a2 = o[dt][4 * g + 2] * inv * silu_f(bflo(gv[1])), a3 = o[dt][4 * g + 3] * inv * silu_f(bfhi(gv[1]));
;       *(u32x2*)q = (u32x2){pack2(a0, a1), pack2(a2, a3)};
;     }
; }
; DI void swa_unit(const Params& p, int u, char* smem, bool probe = false) {
;     ...
;   l += __shfl_xor(l, 32);
;   store_gated(o, 1.f / l, p.G, tok, head);
.LBB0_733:
	v_cmp_lt_i32_e32 vcc, v181, v189
	v_readlane_b32 s12, v230, 51
	v_readlane_b32 s14, v230, 53
	v_cndmask_b32_e32 v0, v202, v181, vcc
	v_lshlrev_b32_e32 v0, 2, v0
	ds_bpermute_b32 v0, v0, v193
	v_readlane_b32 s15, v230, 54
	s_lshl_b32 s58, s10, 22
	s_add_i32 s1, s1, s82
	s_cmpk_gt_i32 s1, 0xfff
	s_waitcnt lgkmcnt(0)
	v_add_f32_e32 v0, v193, v0
	v_div_scale_f32 v34, s[2:3], v0, v0, 1.0
	v_rcp_f32_e32 v35, v34
	v_readlane_b32 s13, v230, 52
	v_readlane_b32 s16, v230, 55
	v_readlane_b32 s17, v230, 56
	v_fma_f32 v36, -v34, v35, 1.0
	v_fmac_f32_e32 v35, v36, v35
	v_div_scale_f32 v36, vcc, 1.0, v0, 1.0
	v_mul_f32_e32 v37, v36, v35
	v_fma_f32 v38, -v34, v37, v36
	v_fmac_f32_e32 v37, v38, v35
	v_fma_f32 v34, -v34, v37, v36
	v_div_fmas_f32 v34, v34, v35, v37
	v_div_fixup_f32 v34, v34, v0, 1.0
	v_mov_b32_e32 v0, v167
	v_lshlrev_b64 v[36:37], 6, v[164:165]
	v_lshl_add_u64 v[36:37], s[14:15], 0, v[36:37]
	v_lshrrev_b32_e32 v0, 2, v0
	v_lshl_add_u64 v[36:37], v[36:37], 0, s[58:59]
	v_and_b32_e32 v0, 8, v0
	v_lshl_add_u64 v[38:39], v[36:37], 0, v[0:1]
	global_load_dwordx2 v[232:233], v[38:39], off
	global_load_dwordx2 v[234:235], v[38:39], off offset:16
	global_load_dwordx2 v[236:237], v[38:39], off offset:32
	global_load_dwordx2 v[238:239], v[38:39], off offset:48
	s_mov_b64 s[100:101], 0x200000
	v_lshl_add_u64 v[248:249], v[38:39], 0, s[100:101]
	global_load_dwordx2 v[240:241], v[248:249], off
	global_load_dwordx2 v[242:243], v[248:249], off offset:16
	global_load_dwordx2 v[244:245], v[248:249], off offset:32
	global_load_dwordx2 v[246:247], v[248:249], off offset:48
	v_readlane_b32 s18, v230, 57
	v_readlane_b32 s19, v230, 58
	v_readlane_b32 s20, v230, 59
	v_readlane_b32 s21, v230, 60
	v_readlane_b32 s22, v230, 61
	v_readlane_b32 s23, v230, 62
	v_readlane_b32 s24, v230, 63
	v_readlane_b32 s25, v229, 0
	v_readlane_b32 s26, v229, 1
	v_readlane_b32 s27, v229, 2
	s_waitcnt vmcnt(7)
	v_mov_b32_e32 v40, v232
	v_mov_b32_e32 v41, v233
	v_lshlrev_b32_e32 v35, 16, v40
	v_and_b32_e32 v40, 0xffff0000, v40
	v_mul_f32_e32 v42, 0xbfb8aa3b, v35
	v_mul_f32_e32 v43, 0xbfb8aa3b, v40
	v_exp_f32_e32 v42, v42
	v_exp_f32_e32 v43, v43
	v_pk_mul_f32 v[2:3], v[2:3], v[34:35] op_sel_hi:[1,0]
	v_pk_add_f32 v[42:43], v[42:43], 1.0 op_sel_hi:[1,0]
	s_nop 0
	v_div_scale_f32 v44, s[2:3], v43, v43, v40
	v_rcp_f32_e32 v45, v44
	s_nop 0
	v_fma_f32 v46, -v44, v45, 1.0
	v_fmac_f32_e32 v45, v46, v45
	v_div_scale_f32 v46, vcc, v40, v43, v40
	v_mul_f32_e32 v47, v46, v45
	v_fma_f32 v48, -v44, v47, v46
	v_fmac_f32_e32 v47, v48, v45
	v_fma_f32 v44, -v44, v47, v46
	v_div_fmas_f32 v44, v44, v45, v47
	v_div_fixup_f32 v43, v44, v43, v40
	v_div_scale_f32 v40, s[2:3], v42, v42, v35
	v_rcp_f32_e32 v44, v40
	s_nop 0
	v_fma_f32 v45, -v40, v44, 1.0
	v_fmac_f32_e32 v44, v45, v44
	v_div_scale_f32 v45, vcc, v35, v42, v35
	v_mul_f32_e32 v46, v45, v44
	v_fma_f32 v47, -v40, v46, v45
	v_fmac_f32_e32 v46, v47, v44
	v_fma_f32 v40, -v40, v46, v45
	v_div_fmas_f32 v40, v40, v44, v46
	v_div_fixup_f32 v42, v40, v42, v35
	v_pk_mul_f32 v[2:3], v[2:3], v[42:43]
	v_lshlrev_b32_e32 v35, 16, v41
	v_and_b32_e32 v42, 0xffff0000, v41
	v_mul_f32_e32 v40, 0xbfb8aa3b, v35
	v_mul_f32_e32 v41, 0xbfb8aa3b, v42
	v_exp_f32_e32 v40, v40
	v_exp_f32_e32 v41, v41
	v_pk_mul_f32 v[4:5], v[4:5], v[34:35] op_sel_hi:[1,0]
	v_cvt_pk_bf16_f32 v2, v2, v3
	v_pk_add_f32 v[40:41], v[40:41], 1.0 op_sel_hi:[1,0]
	s_nop 0
	v_div_scale_f32 v43, s[2:3], v41, v41, v42
	v_rcp_f32_e32 v44, v43
	s_nop 0
	v_fma_f32 v45, -v43, v44, 1.0
	v_fmac_f32_e32 v44, v45, v44
	v_div_scale_f32 v45, vcc, v42, v41, v42
	v_mul_f32_e32 v46, v45, v44
	v_fma_f32 v47, -v43, v46, v45
	v_fmac_f32_e32 v46, v47, v44
	v_fma_f32 v43, -v43, v46, v45
	v_div_fmas_f32 v43, v43, v44, v46
	v_div_fixup_f32 v41, v43, v41, v42
	v_div_scale_f32 v42, s[2:3], v40, v40, v35
	v_rcp_f32_e32 v43, v42
	s_nop 0
	v_fma_f32 v44, -v42, v43, 1.0
	v_fmac_f32_e32 v43, v44, v43
	v_div_scale_f32 v44, vcc, v35, v40, v35
	v_mul_f32_e32 v45, v44, v43
	v_fma_f32 v46, -v42, v45, v44
	v_fmac_f32_e32 v45, v46, v43
	v_fma_f32 v42, -v42, v45, v44
	v_div_fmas_f32 v42, v42, v43, v45
	v_div_fixup_f32 v40, v42, v40, v35
	v_pk_mul_f32 v[4:5], v[4:5], v[40:41]
	s_nop 0
	v_cvt_pk_bf16_f32 v3, v4, v5
	global_store_dwordx2 v[38:39], v[2:3], off
	s_waitcnt vmcnt(7)
	v_mov_b32_e32 v2, v234
	v_mov_b32_e32 v3, v235
	v_lshlrev_b32_e32 v35, 16, v2
	v_and_b32_e32 v2, 0xffff0000, v2
	v_mul_f32_e32 v4, 0xbfb8aa3b, v35
	v_mul_f32_e32 v5, 0xbfb8aa3b, v2
	v_exp_f32_e32 v4, v4
	v_exp_f32_e32 v5, v5
	v_pk_mul_f32 v[6:7], v[6:7], v[34:35] op_sel_hi:[1,0]
	v_pk_add_f32 v[4:5], v[4:5], 1.0 op_sel_hi:[1,0]
	s_nop 0
	v_div_scale_f32 v40, s[2:3], v5, v5, v2
	v_rcp_f32_e32 v41, v40
	s_nop 0
	v_fma_f32 v42, -v40, v41, 1.0
	v_fmac_f32_e32 v41, v42, v41
	v_div_scale_f32 v42, vcc, v2, v5, v2
	v_mul_f32_e32 v43, v42, v41
	v_fma_f32 v44, -v40, v43, v42
	v_fmac_f32_e32 v43, v44, v41
	v_fma_f32 v40, -v40, v43, v42
	v_div_fmas_f32 v40, v40, v41, v43
	v_div_fixup_f32 v5, v40, v5, v2
	v_div_scale_f32 v2, s[2:3], v4, v4, v35
	v_rcp_f32_e32 v40, v2
	s_nop 0
	v_fma_f32 v41, -v2, v40, 1.0
	v_fmac_f32_e32 v40, v41, v40
	v_div_scale_f32 v41, vcc, v35, v4, v35
	v_mul_f32_e32 v42, v41, v40
	v_fma_f32 v43, -v2, v42, v41
	v_fmac_f32_e32 v42, v43, v40
	v_fma_f32 v2, -v2, v42, v41
	v_div_fmas_f32 v2, v2, v40, v42
	v_div_fixup_f32 v4, v2, v4, v35
	v_lshlrev_b32_e32 v35, 16, v3
	v_and_b32_e32 v40, 0xffff0000, v3
	v_mul_f32_e32 v2, 0xbfb8aa3b, v35
	v_mul_f32_e32 v3, 0xbfb8aa3b, v40
	v_exp_f32_e32 v2, v2
	v_exp_f32_e32 v3, v3
	v_pk_mul_f32 v[4:5], v[6:7], v[4:5]
	v_pk_mul_f32 v[6:7], v[8:9], v[34:35] op_sel_hi:[1,0]
	v_cvt_pk_bf16_f32 v4, v4, v5
	v_pk_add_f32 v[2:3], v[2:3], 1.0 op_sel_hi:[1,0]
	s_nop 0
	v_div_scale_f32 v8, s[2:3], v3, v3, v40
	v_rcp_f32_e32 v9, v8
	s_nop 0
	v_fma_f32 v41, -v8, v9, 1.0
	v_fmac_f32_e32 v9, v41, v9
	v_div_scale_f32 v41, vcc, v40, v3, v40
	v_mul_f32_e32 v42, v41, v9
	v_fma_f32 v43, -v8, v42, v41
	v_fmac_f32_e32 v42, v43, v9
	v_fma_f32 v8, -v8, v42, v41
	v_div_fmas_f32 v8, v8, v9, v42
	v_div_fixup_f32 v3, v8, v3, v40
	v_div_scale_f32 v8, s[2:3], v2, v2, v35
	v_rcp_f32_e32 v9, v8
	s_nop 0
	v_fma_f32 v40, -v8, v9, 1.0
	v_fmac_f32_e32 v9, v40, v9
	v_div_scale_f32 v40, vcc, v35, v2, v35
	v_mul_f32_e32 v41, v40, v9
	v_fma_f32 v42, -v8, v41, v40
	v_fmac_f32_e32 v41, v42, v9
	v_fma_f32 v8, -v8, v41, v40
	v_div_fmas_f32 v8, v8, v9, v41
	v_div_fixup_f32 v2, v8, v2, v35
	v_pk_mul_f32 v[2:3], v[6:7], v[2:3]
	v_pk_mul_f32 v[6:7], v[10:11], v[34:35] op_sel_hi:[1,0]
	v_cvt_pk_bf16_f32 v5, v2, v3
	s_waitcnt vmcnt(6)
; DI unsigned pack2(float a, float b) { f32x2 v = {a, b}; bf16x2_t r = __builtin_convertvector(v, bf16x2_t); return __builtin_bit_cast(unsigned, r); }
; DI float bflo(unsigned v) { return __uint_as_float(v << 16); }
; DI float bfhi(unsigned v) { return __uint_as_float(v & 0xffff0000u); }
; DI int otid() { int t = threadIdx.x; asm volatile("" : "+v"(t)); return t; }
; DI size_t blk(size_t row, int k, int R) { return ((size_t)(k >> 5) * R + row) * 32 + (k & 31); }
; DI float silu_f(float x) { return x / (1.f + __expf(-x)); }
; DI void store_gated(const f32x16 (&o)[2], float inv, bf16_t* G, size_t tok, int head) {
;   const int h = (otid() & 63) >> 5;
; #pragma unroll
;   for (int dt = 0; dt < 2; ++dt)
; #pragma unroll
;     for (int g = 0; g < 4; ++g) {
;       bf16_t* q = G + blk(tok, head * 64 + 32 * dt + 8 * g + 4 * h, NTOK);
;       const u32x2 gv = *(const u32x2*)q;
;       const float a0 = o[dt][4 * g] * inv * silu_f(bflo(gv[0])), a1 = o[dt][4 * g + 1] * inv * silu_f(bfhi(gv[0]));
;       const float a2 = o[dt][4 * g + 2] * inv * silu_f(bflo(gv[1])), a3 = o[dt][4 * g + 3] * inv * silu_f(bfhi(gv[1]));
;       *(u32x2*)q = (u32x2){pack2(a0, a1), pack2(a2, a3)};
;     }
; }
	v_mov_b32_e32 v2, v236
	v_mov_b32_e32 v3, v237
	v_lshlrev_b32_e32 v8, 16, v2
	v_and_b32_e32 v2, 0xffff0000, v2
	global_store_dwordx2 v[38:39], v[4:5], off offset:16
	v_mul_f32_e32 v4, 0xbfb8aa3b, v8
	v_mul_f32_e32 v5, 0xbfb8aa3b, v2
	v_exp_f32_e32 v4, v4
	v_exp_f32_e32 v5, v5
	s_nop 0
	v_pk_add_f32 v[4:5], v[4:5], 1.0 op_sel_hi:[1,0]
	s_nop 0
	v_div_scale_f32 v9, s[2:3], v5, v5, v2
	v_rcp_f32_e32 v10, v9
	s_nop 0
	v_fma_f32 v11, -v9, v10, 1.0
	v_fmac_f32_e32 v10, v11, v10
	v_div_scale_f32 v11, vcc, v2, v5, v2
	v_mul_f32_e32 v35, v11, v10
	v_fma_f32 v40, -v9, v35, v11
	v_fmac_f32_e32 v35, v40, v10
	v_fma_f32 v9, -v9, v35, v11
	v_div_fmas_f32 v9, v9, v10, v35
	v_div_fixup_f32 v5, v9, v5, v2
	v_div_scale_f32 v2, s[2:3], v4, v4, v8
	v_rcp_f32_e32 v9, v2
	s_nop 0
	v_fma_f32 v10, -v2, v9, 1.0
	v_fmac_f32_e32 v9, v10, v9
	v_div_scale_f32 v10, vcc, v8, v4, v8
	v_mul_f32_e32 v11, v10, v9
	v_fma_f32 v35, -v2, v11, v10
	v_fmac_f32_e32 v11, v35, v9
	v_fma_f32 v2, -v2, v11, v10
	v_div_fmas_f32 v2, v2, v9, v11
	v_div_fixup_f32 v4, v2, v4, v8
	v_lshlrev_b32_e32 v8, 16, v3
	v_and_b32_e32 v9, 0xffff0000, v3
	v_mul_f32_e32 v2, 0xbfb8aa3b, v8
	v_mul_f32_e32 v3, 0xbfb8aa3b, v9
	v_exp_f32_e32 v2, v2
	v_exp_f32_e32 v3, v3
	v_pk_mul_f32 v[4:5], v[6:7], v[4:5]
	v_pk_mul_f32 v[6:7], v[12:13], v[34:35] op_sel_hi:[1,0]
	v_cvt_pk_bf16_f32 v4, v4, v5
	v_pk_add_f32 v[2:3], v[2:3], 1.0 op_sel_hi:[1,0]
	s_nop 0
	v_div_scale_f32 v10, s[2:3], v3, v3, v9
	v_rcp_f32_e32 v11, v10
	s_nop 0
	v_fma_f32 v12, -v10, v11, 1.0
	v_fmac_f32_e32 v11, v12, v11
	v_div_scale_f32 v12, vcc, v9, v3, v9
	v_mul_f32_e32 v13, v12, v11
	v_fma_f32 v35, -v10, v13, v12
	v_fmac_f32_e32 v13, v35, v11
	v_fma_f32 v10, -v10, v13, v12
	v_div_fmas_f32 v10, v10, v11, v13
	v_div_fixup_f32 v3, v10, v3, v9
	v_div_scale_f32 v9, s[2:3], v2, v2, v8
	v_rcp_f32_e32 v10, v9
	s_nop 0
	v_fma_f32 v11, -v9, v10, 1.0
	v_fmac_f32_e32 v10, v11, v10
	v_div_scale_f32 v11, vcc, v8, v2, v8
	v_mul_f32_e32 v12, v11, v10
	v_fma_f32 v13, -v9, v12, v11
	v_fmac_f32_e32 v12, v13, v10
	v_fma_f32 v9, -v9, v12, v11
	v_div_fmas_f32 v9, v9, v10, v12
	v_div_fixup_f32 v2, v9, v2, v8
	v_pk_mul_f32 v[2:3], v[6:7], v[2:3]
	v_pk_mul_f32 v[6:7], v[14:15], v[34:35] op_sel_hi:[1,0]
	v_cvt_pk_bf16_f32 v5, v2, v3
	s_waitcnt vmcnt(6)
	v_mov_b32_e32 v2, v238
	v_mov_b32_e32 v3, v239
	v_lshlrev_b32_e32 v8, 16, v2
	v_and_b32_e32 v2, 0xffff0000, v2
	global_store_dwordx2 v[38:39], v[4:5], off offset:32
	v_mul_f32_e32 v4, 0xbfb8aa3b, v8
	v_mul_f32_e32 v5, 0xbfb8aa3b, v2
	v_exp_f32_e32 v4, v4
	v_exp_f32_e32 v5, v5
	s_nop 0
	v_pk_add_f32 v[4:5], v[4:5], 1.0 op_sel_hi:[1,0]
	s_nop 0
	v_div_scale_f32 v9, s[2:3], v5, v5, v2
	v_rcp_f32_e32 v10, v9
	s_nop 0
	v_fma_f32 v11, -v9, v10, 1.0
	v_fmac_f32_e32 v10, v11, v10
	v_div_scale_f32 v11, vcc, v2, v5, v2
	v_mul_f32_e32 v12, v11, v10
	v_fma_f32 v13, -v9, v12, v11
	v_fmac_f32_e32 v12, v13, v10
	v_fma_f32 v9, -v9, v12, v11
	v_div_fmas_f32 v9, v9, v10, v12
	v_div_fixup_f32 v5, v9, v5, v2
	v_div_scale_f32 v2, s[2:3], v4, v4, v8
	v_rcp_f32_e32 v9, v2
	s_nop 0
	v_fma_f32 v10, -v2, v9, 1.0
	v_fmac_f32_e32 v9, v10, v9
	v_div_scale_f32 v10, vcc, v8, v4, v8
	v_mul_f32_e32 v11, v10, v9
	v_fma_f32 v12, -v2, v11, v10
	v_fmac_f32_e32 v11, v12, v9
	v_fma_f32 v2, -v2, v11, v10
	v_div_fmas_f32 v2, v2, v9, v11
	v_div_fixup_f32 v4, v2, v4, v8
	v_lshlrev_b32_e32 v8, 16, v3
	v_and_b32_e32 v9, 0xffff0000, v3
	v_mul_f32_e32 v2, 0xbfb8aa3b, v8
	v_mul_f32_e32 v3, 0xbfb8aa3b, v9
	v_exp_f32_e32 v2, v2
	v_exp_f32_e32 v3, v3
	v_pk_mul_f32 v[4:5], v[6:7], v[4:5]
	v_pk_mul_f32 v[6:7], v[16:17], v[34:35] op_sel_hi:[1,0]
	v_cvt_pk_bf16_f32 v4, v4, v5
	v_pk_add_f32 v[2:3], v[2:3], 1.0 op_sel_hi:[1,0]
	s_nop 0
	v_div_scale_f32 v10, s[2:3], v3, v3, v9
	v_rcp_f32_e32 v11, v10
	s_nop 0
	v_fma_f32 v12, -v10, v11, 1.0
	v_fmac_f32_e32 v11, v12, v11
	v_div_scale_f32 v12, vcc, v9, v3, v9
	v_mul_f32_e32 v13, v12, v11
	v_fma_f32 v14, -v10, v13, v12
	v_fmac_f32_e32 v13, v14, v11
	v_fma_f32 v10, -v10, v13, v12
	v_div_fmas_f32 v10, v10, v11, v13
	v_div_fixup_f32 v3, v10, v3, v9
	v_div_scale_f32 v9, s[2:3], v2, v2, v8
	v_rcp_f32_e32 v10, v9
	s_nop 0
	v_fma_f32 v11, -v9, v10, 1.0
	v_fmac_f32_e32 v10, v11, v10
	v_div_scale_f32 v11, vcc, v8, v2, v8
	v_mul_f32_e32 v12, v11, v10
	v_fma_f32 v13, -v9, v12, v11
	v_fmac_f32_e32 v12, v13, v10
	v_fma_f32 v9, -v9, v12, v11
	v_div_fmas_f32 v9, v9, v10, v12
	v_div_fixup_f32 v2, v9, v2, v8
	v_pk_mul_f32 v[2:3], v[6:7], v[2:3]
	v_pk_mul_f32 v[10:11], v[18:19], v[34:35] op_sel_hi:[1,0]
	v_cvt_pk_bf16_f32 v5, v2, v3
	v_lshl_add_u64 v[2:3], v[36:37], 0, s[88:89]
	global_store_dwordx2 v[38:39], v[4:5], off offset:48
	v_lshl_add_u64 v[4:5], v[2:3], 0, v[0:1]
	s_waitcnt vmcnt(7)
; DI unsigned pack2(float a, float b) { f32x2 v = {a, b}; bf16x2_t r = __builtin_convertvector(v, bf16x2_t); return __builtin_bit_cast(unsigned, r); }
; DI float bflo(unsigned v) { return __uint_as_float(v << 16); }
; DI float bfhi(unsigned v) { return __uint_as_float(v & 0xffff0000u); }
; DI int otid() { int t = threadIdx.x; asm volatile("" : "+v"(t)); return t; }
; DI size_t blk(size_t row, int k, int R) { return ((size_t)(k >> 5) * R + row) * 32 + (k & 31); }
; DI float silu_f(float x) { return x / (1.f + __expf(-x)); }
; DI void store_gated(const f32x16 (&o)[2], float inv, bf16_t* G, size_t tok, int head) {
;   const int h = (otid() & 63) >> 5;
; #pragma unroll
;   for (int dt = 0; dt < 2; ++dt)
; #pragma unroll
;     for (int g = 0; g < 4; ++g) {
;       bf16_t* q = G + blk(tok, head * 64 + 32 * dt + 8 * g + 4 * h, NTOK);
;       const u32x2 gv = *(const u32x2*)q;
;       const float a0 = o[dt][4 * g] * inv * silu_f(bflo(gv[0])), a1 = o[dt][4 * g + 1] * inv * silu_f(bfhi(gv[0]));
;       const float a2 = o[dt][4 * g + 2] * inv * silu_f(bflo(gv[1])), a3 = o[dt][4 * g + 3] * inv * silu_f(bfhi(gv[1]));
;       *(u32x2*)q = (u32x2){pack2(a0, a1), pack2(a2, a3)};
;     }
; }
	v_mov_b32_e32 v6, v240
	v_mov_b32_e32 v7, v241
	v_lshlrev_b32_e32 v12, 16, v6
	v_and_b32_e32 v6, 0xffff0000, v6
	v_mul_f32_e32 v8, 0xbfb8aa3b, v12
	v_mul_f32_e32 v9, 0xbfb8aa3b, v6
	v_exp_f32_e32 v8, v8
	v_exp_f32_e32 v9, v9
	s_nop 0
	v_pk_add_f32 v[8:9], v[8:9], 1.0 op_sel_hi:[1,0]
	s_nop 0
	v_div_scale_f32 v13, s[2:3], v9, v9, v6
	v_rcp_f32_e32 v14, v13
	s_nop 0
	v_fma_f32 v15, -v13, v14, 1.0
	v_fmac_f32_e32 v14, v15, v14
	v_div_scale_f32 v15, vcc, v6, v9, v6
	v_mul_f32_e32 v16, v15, v14
	v_fma_f32 v17, -v13, v16, v15
	v_fmac_f32_e32 v16, v17, v14
	v_fma_f32 v13, -v13, v16, v15
	v_div_fmas_f32 v13, v13, v14, v16
	v_div_fixup_f32 v9, v13, v9, v6
	v_div_scale_f32 v6, s[2:3], v8, v8, v12
	v_rcp_f32_e32 v13, v6
	s_nop 0
	v_fma_f32 v14, -v6, v13, 1.0
	v_fmac_f32_e32 v13, v14, v13
	v_div_scale_f32 v14, vcc, v12, v8, v12
	v_mul_f32_e32 v15, v14, v13
	v_fma_f32 v16, -v6, v15, v14
	v_fmac_f32_e32 v15, v16, v13
	v_fma_f32 v6, -v6, v15, v14
	v_div_fmas_f32 v6, v6, v13, v15
	v_div_fixup_f32 v8, v6, v8, v12
	v_lshlrev_b32_e32 v12, 16, v7
	v_and_b32_e32 v13, 0xffff0000, v7
	v_mul_f32_e32 v6, 0xbfb8aa3b, v12
	v_mul_f32_e32 v7, 0xbfb8aa3b, v13
	v_exp_f32_e32 v6, v6
	v_exp_f32_e32 v7, v7
	v_pk_mul_f32 v[8:9], v[10:11], v[8:9]
	v_pk_mul_f32 v[10:11], v[20:21], v[34:35] op_sel_hi:[1,0]
	v_cvt_pk_bf16_f32 v8, v8, v9
	v_pk_add_f32 v[6:7], v[6:7], 1.0 op_sel_hi:[1,0]
	s_nop 0
	v_div_scale_f32 v14, s[2:3], v7, v7, v13
	v_rcp_f32_e32 v15, v14
	s_nop 0
	v_fma_f32 v16, -v14, v15, 1.0
	v_fmac_f32_e32 v15, v16, v15
	v_div_scale_f32 v16, vcc, v13, v7, v13
	v_mul_f32_e32 v17, v16, v15
	v_fma_f32 v18, -v14, v17, v16
	v_fmac_f32_e32 v17, v18, v15
	v_fma_f32 v14, -v14, v17, v16
	v_div_fmas_f32 v14, v14, v15, v17
	v_div_fixup_f32 v7, v14, v7, v13
	v_div_scale_f32 v13, s[2:3], v6, v6, v12
	v_rcp_f32_e32 v14, v13
	s_nop 0
	v_fma_f32 v15, -v13, v14, 1.0
	v_fmac_f32_e32 v14, v15, v14
	v_div_scale_f32 v15, vcc, v12, v6, v12
	v_mul_f32_e32 v16, v15, v14
	v_fma_f32 v17, -v13, v16, v15
	v_fmac_f32_e32 v16, v17, v14
	v_fma_f32 v13, -v13, v16, v15
	v_div_fmas_f32 v13, v13, v14, v16
	v_div_fixup_f32 v6, v13, v6, v12
	v_pk_mul_f32 v[6:7], v[10:11], v[6:7]
	v_pk_mul_f32 v[10:11], v[22:23], v[34:35] op_sel_hi:[1,0]
	v_cvt_pk_bf16_f32 v9, v6, v7
	global_store_dwordx2 v[4:5], v[8:9], off
	v_or_b32_e32 v4, 16, v0
	v_mov_b32_e32 v5, v1
	v_lshl_add_u64 v[4:5], v[2:3], 0, v[4:5]
	s_waitcnt vmcnt(7)
	v_mov_b32_e32 v6, v242
	v_mov_b32_e32 v7, v243
	v_lshlrev_b32_e32 v12, 16, v6
	v_and_b32_e32 v6, 0xffff0000, v6
	v_mul_f32_e32 v8, 0xbfb8aa3b, v12
	v_mul_f32_e32 v9, 0xbfb8aa3b, v6
	v_exp_f32_e32 v8, v8
	v_exp_f32_e32 v9, v9
	s_nop 0
	v_pk_add_f32 v[8:9], v[8:9], 1.0 op_sel_hi:[1,0]
	s_nop 0
	v_div_scale_f32 v13, s[2:3], v9, v9, v6
	v_rcp_f32_e32 v14, v13
	s_nop 0
	v_fma_f32 v15, -v13, v14, 1.0
	v_fmac_f32_e32 v14, v15, v14
	v_div_scale_f32 v15, vcc, v6, v9, v6
	v_mul_f32_e32 v16, v15, v14
	v_fma_f32 v17, -v13, v16, v15
	v_fmac_f32_e32 v16, v17, v14
	v_fma_f32 v13, -v13, v16, v15
	v_div_fmas_f32 v13, v13, v14, v16
	v_div_fixup_f32 v9, v13, v9, v6
	v_div_scale_f32 v6, s[2:3], v8, v8, v12
	v_rcp_f32_e32 v13, v6
	s_nop 0
	v_fma_f32 v14, -v6, v13, 1.0
	v_fmac_f32_e32 v13, v14, v13
	v_div_scale_f32 v14, vcc, v12, v8, v12
	v_mul_f32_e32 v15, v14, v13
	v_fma_f32 v16, -v6, v15, v14
	v_fmac_f32_e32 v15, v16, v13
	v_fma_f32 v6, -v6, v15, v14
	v_div_fmas_f32 v6, v6, v13, v15
	v_div_fixup_f32 v8, v6, v8, v12
	v_lshlrev_b32_e32 v12, 16, v7
	v_and_b32_e32 v13, 0xffff0000, v7
	v_mul_f32_e32 v6, 0xbfb8aa3b, v12
	v_mul_f32_e32 v7, 0xbfb8aa3b, v13
	v_exp_f32_e32 v6, v6
	v_exp_f32_e32 v7, v7
	v_pk_mul_f32 v[8:9], v[10:11], v[8:9]
	v_pk_mul_f32 v[10:11], v[24:25], v[34:35] op_sel_hi:[1,0]
	v_cvt_pk_bf16_f32 v8, v8, v9
	v_pk_add_f32 v[6:7], v[6:7], 1.0 op_sel_hi:[1,0]
	s_nop 0
	v_div_scale_f32 v14, s[2:3], v7, v7, v13
	v_rcp_f32_e32 v15, v14
	s_nop 0
	v_fma_f32 v16, -v14, v15, 1.0
	v_fmac_f32_e32 v15, v16, v15
	v_div_scale_f32 v16, vcc, v13, v7, v13
	v_mul_f32_e32 v17, v16, v15
	v_fma_f32 v18, -v14, v17, v16
	v_fmac_f32_e32 v17, v18, v15
	v_fma_f32 v14, -v14, v17, v16
	v_div_fmas_f32 v14, v14, v15, v17
	v_div_fixup_f32 v7, v14, v7, v13
	v_div_scale_f32 v13, s[2:3], v6, v6, v12
	v_rcp_f32_e32 v14, v13
	s_nop 0
	v_fma_f32 v15, -v13, v14, 1.0
	v_fmac_f32_e32 v14, v15, v14
	v_div_scale_f32 v15, vcc, v12, v6, v12
	v_mul_f32_e32 v16, v15, v14
	v_fma_f32 v17, -v13, v16, v15
	v_fmac_f32_e32 v16, v17, v14
	v_fma_f32 v13, -v13, v16, v15
	v_div_fmas_f32 v13, v13, v14, v16
	v_div_fixup_f32 v6, v13, v6, v12
	v_pk_mul_f32 v[6:7], v[10:11], v[6:7]
	v_pk_mul_f32 v[10:11], v[26:27], v[34:35] op_sel_hi:[1,0]
	v_cvt_pk_bf16_f32 v9, v6, v7
	global_store_dwordx2 v[4:5], v[8:9], off
	v_or_b32_e32 v4, 32, v0
	v_mov_b32_e32 v5, v1
	v_lshl_add_u64 v[4:5], v[2:3], 0, v[4:5]
	v_or_b32_e32 v0, 48, v0
	v_lshl_add_u64 v[2:3], v[2:3], 0, v[0:1]
	s_waitcnt vmcnt(7)
; DI unsigned pack2(float a, float b) { f32x2 v = {a, b}; bf16x2_t r = __builtin_convertvector(v, bf16x2_t); return __builtin_bit_cast(unsigned, r); }
; DI float bflo(unsigned v) { return __uint_as_float(v << 16); }
; DI float bfhi(unsigned v) { return __uint_as_float(v & 0xffff0000u); }
; DI int otid() { int t = threadIdx.x; asm volatile("" : "+v"(t)); return t; }
; DI size_t blk(size_t row, int k, int R) { return ((size_t)(k >> 5) * R + row) * 32 + (k & 31); }
; DI float silu_f(float x) { return x / (1.f + __expf(-x)); }
; DI void store_gated(const f32x16 (&o)[2], float inv, bf16_t* G, size_t tok, int head) {
;   const int h = (otid() & 63) >> 5;
; #pragma unroll
;   for (int dt = 0; dt < 2; ++dt)
; #pragma unroll
;     for (int g = 0; g < 4; ++g) {
;       bf16_t* q = G + blk(tok, head * 64 + 32 * dt + 8 * g + 4 * h, NTOK);
;       const u32x2 gv = *(const u32x2*)q;
;       const float a0 = o[dt][4 * g] * inv * silu_f(bflo(gv[0])), a1 = o[dt][4 * g + 1] * inv * silu_f(bfhi(gv[0]));
;       const float a2 = o[dt][4 * g + 2] * inv * silu_f(bflo(gv[1])), a3 = o[dt][4 * g + 3] * inv * silu_f(bfhi(gv[1]));
;       *(u32x2*)q = (u32x2){pack2(a0, a1), pack2(a2, a3)};
;     }
; }
; DI void swa_unit(const Params& p, int u, char* smem, bool probe = false) {
;     ...
;   l += __shfl_xor(l, 32);
;   store_gated(o, 1.f / l, p.G, tok, head);
	v_mov_b32_e32 v6, v244
	v_mov_b32_e32 v7, v245
	v_lshlrev_b32_e32 v12, 16, v6
	v_and_b32_e32 v6, 0xffff0000, v6
	v_mul_f32_e32 v8, 0xbfb8aa3b, v12
	v_mul_f32_e32 v9, 0xbfb8aa3b, v6
	v_exp_f32_e32 v8, v8
	v_exp_f32_e32 v9, v9
	s_nop 0
	v_pk_add_f32 v[8:9], v[8:9], 1.0 op_sel_hi:[1,0]
	s_nop 0
	v_div_scale_f32 v13, s[2:3], v9, v9, v6
	v_rcp_f32_e32 v14, v13
	s_nop 0
	v_fma_f32 v15, -v13, v14, 1.0
	v_fmac_f32_e32 v14, v15, v14
	v_div_scale_f32 v15, vcc, v6, v9, v6
	v_mul_f32_e32 v16, v15, v14
	v_fma_f32 v17, -v13, v16, v15
	v_fmac_f32_e32 v16, v17, v14
	v_fma_f32 v13, -v13, v16, v15
	v_div_fmas_f32 v13, v13, v14, v16
	v_div_fixup_f32 v9, v13, v9, v6
	v_div_scale_f32 v6, s[2:3], v8, v8, v12
	v_rcp_f32_e32 v13, v6
	s_nop 0
	v_fma_f32 v14, -v6, v13, 1.0
	v_fmac_f32_e32 v13, v14, v13
	v_div_scale_f32 v14, vcc, v12, v8, v12
	v_mul_f32_e32 v15, v14, v13
	v_fma_f32 v16, -v6, v15, v14
	v_fmac_f32_e32 v15, v16, v13
	v_fma_f32 v6, -v6, v15, v14
	v_div_fmas_f32 v6, v6, v13, v15
	v_div_fixup_f32 v8, v6, v8, v12
	v_lshlrev_b32_e32 v12, 16, v7
	v_and_b32_e32 v13, 0xffff0000, v7
	v_mul_f32_e32 v6, 0xbfb8aa3b, v12
	v_mul_f32_e32 v7, 0xbfb8aa3b, v13
	v_exp_f32_e32 v6, v6
	v_exp_f32_e32 v7, v7
	v_pk_mul_f32 v[8:9], v[10:11], v[8:9]
	v_pk_mul_f32 v[10:11], v[28:29], v[34:35] op_sel_hi:[1,0]
	v_cvt_pk_bf16_f32 v8, v8, v9
	v_pk_add_f32 v[6:7], v[6:7], 1.0 op_sel_hi:[1,0]
	s_nop 0
	v_div_scale_f32 v14, s[2:3], v7, v7, v13
	v_rcp_f32_e32 v15, v14
	s_nop 0
	v_fma_f32 v16, -v14, v15, 1.0
	v_fmac_f32_e32 v15, v16, v15
	v_div_scale_f32 v16, vcc, v13, v7, v13
	v_mul_f32_e32 v17, v16, v15
	v_fma_f32 v18, -v14, v17, v16
	v_fmac_f32_e32 v17, v18, v15
	v_fma_f32 v14, -v14, v17, v16
	v_div_fmas_f32 v14, v14, v15, v17
	v_div_fixup_f32 v7, v14, v7, v13
	v_div_scale_f32 v13, s[2:3], v6, v6, v12
	v_rcp_f32_e32 v14, v13
	s_nop 0
	v_fma_f32 v15, -v13, v14, 1.0
	v_fmac_f32_e32 v14, v15, v14
	v_div_scale_f32 v15, vcc, v12, v6, v12
	v_mul_f32_e32 v16, v15, v14
	v_fma_f32 v17, -v13, v16, v15
	v_fmac_f32_e32 v16, v17, v14
	v_fma_f32 v13, -v13, v16, v15
	v_div_fmas_f32 v13, v13, v14, v16
	v_div_fixup_f32 v6, v13, v6, v12
	v_pk_mul_f32 v[6:7], v[10:11], v[6:7]
	s_nop 0
	v_cvt_pk_bf16_f32 v9, v6, v7
	global_store_dwordx2 v[4:5], v[8:9], off
	v_pk_mul_f32 v[8:9], v[30:31], v[34:35] op_sel_hi:[1,0]
	s_waitcnt vmcnt(7)
	v_mov_b32_e32 v4, v246
	v_mov_b32_e32 v5, v247
	v_lshlrev_b32_e32 v0, 16, v4
	v_and_b32_e32 v4, 0xffff0000, v4
	v_mul_f32_e32 v6, 0xbfb8aa3b, v0
	v_mul_f32_e32 v7, 0xbfb8aa3b, v4
	v_exp_f32_e32 v6, v6
	v_exp_f32_e32 v7, v7
	s_nop 0
	v_pk_add_f32 v[6:7], v[6:7], 1.0 op_sel_hi:[1,0]
	s_nop 0
	v_div_scale_f32 v10, s[2:3], v7, v7, v4
	v_rcp_f32_e32 v11, v10
	s_nop 0
	v_fma_f32 v12, -v10, v11, 1.0
	v_fmac_f32_e32 v11, v12, v11
	v_div_scale_f32 v12, vcc, v4, v7, v4
	v_mul_f32_e32 v13, v12, v11
	v_fma_f32 v14, -v10, v13, v12
	v_fmac_f32_e32 v13, v14, v11
	v_fma_f32 v10, -v10, v13, v12
	v_div_fmas_f32 v10, v10, v11, v13
	v_div_fixup_f32 v7, v10, v7, v4
	v_div_scale_f32 v4, s[2:3], v6, v6, v0
	v_rcp_f32_e32 v10, v4
	s_nop 0
	v_fma_f32 v11, -v4, v10, 1.0
	v_fmac_f32_e32 v10, v11, v10
	v_div_scale_f32 v11, vcc, v0, v6, v0
	v_mul_f32_e32 v12, v11, v10
	v_fma_f32 v13, -v4, v12, v11
	v_fmac_f32_e32 v12, v13, v10
	v_fma_f32 v4, -v4, v12, v11
	v_div_fmas_f32 v4, v4, v10, v12
	v_div_fixup_f32 v6, v4, v6, v0
	v_lshlrev_b32_e32 v0, 16, v5
	v_and_b32_e32 v10, 0xffff0000, v5
	v_mul_f32_e32 v4, 0xbfb8aa3b, v0
	v_mul_f32_e32 v5, 0xbfb8aa3b, v10
	v_exp_f32_e32 v4, v4
	v_exp_f32_e32 v5, v5
	v_pk_mul_f32 v[6:7], v[8:9], v[6:7]
	v_pk_mul_f32 v[8:9], v[32:33], v[34:35] op_sel_hi:[1,0]
	v_cvt_pk_bf16_f32 v6, v6, v7
	v_pk_add_f32 v[4:5], v[4:5], 1.0 op_sel_hi:[1,0]
	s_nop 0
	v_div_scale_f32 v11, s[2:3], v5, v5, v10
	v_rcp_f32_e32 v12, v11
	s_nop 0
	v_fma_f32 v13, -v11, v12, 1.0
	v_fmac_f32_e32 v12, v13, v12
	v_div_scale_f32 v13, vcc, v10, v5, v10
	v_mul_f32_e32 v14, v13, v12
	v_fma_f32 v15, -v11, v14, v13
	v_fmac_f32_e32 v14, v15, v12
	v_fma_f32 v11, -v11, v14, v13
	v_div_fmas_f32 v11, v11, v12, v14
	v_div_fixup_f32 v5, v11, v5, v10
	v_div_scale_f32 v10, s[2:3], v4, v4, v0
	v_rcp_f32_e32 v11, v10
	s_nop 0
	v_fma_f32 v12, -v10, v11, 1.0
	v_fmac_f32_e32 v11, v12, v11
	v_div_scale_f32 v12, vcc, v0, v4, v0
	v_mul_f32_e32 v13, v12, v11
	v_fma_f32 v14, -v10, v13, v12
	v_fmac_f32_e32 v13, v14, v11
	v_fma_f32 v10, -v10, v13, v12
	v_div_fmas_f32 v10, v10, v11, v13
	v_div_fixup_f32 v4, v10, v4, v0
	v_pk_mul_f32 v[4:5], v[8:9], v[4:5]
	s_nop 0
	v_cvt_pk_bf16_f32 v7, v4, v5
	global_store_dwordx2 v[2:3], v[6:7], off
	s_cbranch_scc1 .LBB0_848

; DI unsigned pack2(float a, float b) { f32x2 v = {a, b}; bf16x2_t r = __builtin_convertvector(v, bf16x2_t); return __builtin_bit_cast(unsigned, r); }
; DI float bflo(unsigned v) { return __uint_as_float(v << 16); }
; DI float bfhi(unsigned v) { return __uint_as_float(v & 0xffff0000u); }
; DI int otid() { int t = threadIdx.x; asm volatile("" : "+v"(t)); return t; }
; DI size_t blk(size_t row, int k, int R) { return ((size_t)(k >> 5) * R + row) * 32 + (k & 31); }
; DI float silu_f(float x) { return x / (1.f + __expf(-x)); }
; DI void store_gated(const f32x16 (&o)[2], float inv, bf16_t* G, size_t tok, int head) {
;   const int h = (otid() & 63) >> 5;
; #pragma unroll
;   for (int dt = 0; dt < 2; ++dt)
; #pragma unroll
;     for (int g = 0; g < 4; ++g) {
;       bf16_t* q = G + blk(tok, head * 64 + 32 * dt + 8 * g + 4 * h, NTOK);
;       const u32x2 gv = *(const u32x2*)q;
;       const float a0 = o[dt][4 * g] * inv * silu_f(bflo(gv[0])), a1 = o[dt][4 * g + 1] * inv * silu_f(bfhi(gv[0]));
;       const float a2 = o[dt][4 * g + 2] * inv * silu_f(bflo(gv[1])), a3 = o[dt][4 * g + 3] * inv * silu_f(bfhi(gv[1]));
;       *(u32x2*)q = (u32x2){pack2(a0, a1), pack2(a2, a3)};
;     }
; }
; DI void fox_unit(const Params& p, int u, char* smem, bool probe = false) {
;     ...
;   l += __shfl_xor(l, 32);
;   store_gated(o, 1.f / l, p.G, tok, hd);
.LBB0_981:
	v_and_b32_e32 v34, 64, v202
	v_xor_b32_e32 v0, 32, v202
	v_add_u32_e32 v34, 64, v34
	v_cmp_lt_i32_e32 vcc, v0, v34
	s_lshl_b32 s2, s2, 1
	s_ashr_i32 s3, s2, 31
	v_cndmask_b32_e32 v0, v202, v0, vcc
	v_lshlrev_b32_e32 v0, 2, v0
	ds_bpermute_b32 v0, v0, v159
	s_add_i32 s1, s1, s82
	s_waitcnt lgkmcnt(0)
	v_add_f32_e32 v0, v159, v0
	v_div_scale_f32 v34, s[4:5], v0, v0, 1.0
	v_rcp_f32_e32 v35, v34
	v_readlane_b32 s4, v230, 51
	v_readlane_b32 s5, v230, 52
	v_readlane_b32 s6, v230, 53
	v_fma_f32 v36, -v34, v35, 1.0
	v_fmac_f32_e32 v35, v36, v35
	v_div_scale_f32 v36, vcc, 1.0, v0, 1.0
	v_mul_f32_e32 v37, v36, v35
	v_fma_f32 v38, -v34, v37, v36
	v_fmac_f32_e32 v37, v38, v35
	v_fma_f32 v34, -v34, v37, v36
	v_div_fmas_f32 v34, v34, v35, v37
	v_div_fixup_f32 v34, v34, v0, 1.0
	v_mov_b32_e32 v0, v167
	v_lshlrev_b64 v[36:37], 6, v[146:147]
	v_readlane_b32 s7, v230, 54
	s_lshl_b64 s[4:5], s[2:3], 21
	v_lshrrev_b32_e32 v0, 2, v0
	v_lshl_add_u64 v[36:37], s[6:7], 0, v[36:37]
	v_lshl_add_u64 v[38:39], v[36:37], 0, s[4:5]
	v_and_b32_e32 v0, 8, v0
	v_lshl_add_u64 v[38:39], v[38:39], 0, v[0:1]
	global_load_dwordx2 v[232:233], v[38:39], off
	global_load_dwordx2 v[234:235], v[38:39], off offset:16
	global_load_dwordx2 v[236:237], v[38:39], off offset:32
	global_load_dwordx2 v[238:239], v[38:39], off offset:48
	s_mov_b64 s[100:101], 0x200000
	v_lshl_add_u64 v[248:249], v[38:39], 0, s[100:101]
	global_load_dwordx2 v[240:241], v[248:249], off
	global_load_dwordx2 v[242:243], v[248:249], off offset:16
	global_load_dwordx2 v[244:245], v[248:249], off offset:32
	global_load_dwordx2 v[246:247], v[248:249], off offset:48
	s_or_b32 s2, s2, 1
	s_ashr_i32 s3, s2, 31
	s_lshl_b64 s[2:3], s[2:3], 21
	s_cmpk_gt_i32 s1, 0xfff
	v_readlane_b32 s8, v230, 55
	v_readlane_b32 s9, v230, 56
	v_readlane_b32 s10, v230, 57
	v_readlane_b32 s11, v230, 58
	v_readlane_b32 s12, v230, 59
	v_readlane_b32 s13, v230, 60
	v_readlane_b32 s14, v230, 61
	v_readlane_b32 s15, v230, 62
	v_readlane_b32 s16, v230, 63
	v_readlane_b32 s17, v229, 0
	v_readlane_b32 s18, v229, 1
	v_readlane_b32 s19, v229, 2
	s_waitcnt vmcnt(7)
	v_mov_b32_e32 v40, v232
	v_mov_b32_e32 v41, v233
	v_lshlrev_b32_e32 v35, 16, v40
	v_and_b32_e32 v40, 0xffff0000, v40
	v_mul_f32_e32 v42, 0xbfb8aa3b, v35
	v_mul_f32_e32 v43, 0xbfb8aa3b, v40
	v_exp_f32_e32 v42, v42
	v_exp_f32_e32 v43, v43
	v_pk_mul_f32 v[2:3], v[2:3], v[34:35] op_sel_hi:[1,0]
	v_pk_add_f32 v[42:43], v[42:43], 1.0 op_sel_hi:[1,0]
	s_nop 0
	v_div_scale_f32 v44, s[4:5], v43, v43, v40
	v_rcp_f32_e32 v45, v44
	s_nop 0
	v_fma_f32 v46, -v44, v45, 1.0
	v_fmac_f32_e32 v45, v46, v45
	v_div_scale_f32 v46, vcc, v40, v43, v40
	v_mul_f32_e32 v47, v46, v45
	v_fma_f32 v48, -v44, v47, v46
	v_fmac_f32_e32 v47, v48, v45
	v_fma_f32 v44, -v44, v47, v46
	v_div_fmas_f32 v44, v44, v45, v47
	v_div_fixup_f32 v43, v44, v43, v40
	v_div_scale_f32 v40, s[4:5], v42, v42, v35
	v_rcp_f32_e32 v44, v40
	s_nop 0
	v_fma_f32 v45, -v40, v44, 1.0
	v_fmac_f32_e32 v44, v45, v44
	v_div_scale_f32 v45, vcc, v35, v42, v35
	v_mul_f32_e32 v46, v45, v44
	v_fma_f32 v47, -v40, v46, v45
	v_fmac_f32_e32 v46, v47, v44
	v_fma_f32 v40, -v40, v46, v45
	v_div_fmas_f32 v40, v40, v44, v46
	v_div_fixup_f32 v42, v40, v42, v35
	v_pk_mul_f32 v[2:3], v[2:3], v[42:43]
	v_lshlrev_b32_e32 v35, 16, v41
	v_and_b32_e32 v42, 0xffff0000, v41
	v_mul_f32_e32 v40, 0xbfb8aa3b, v35
	v_mul_f32_e32 v41, 0xbfb8aa3b, v42
	v_exp_f32_e32 v40, v40
	v_exp_f32_e32 v41, v41
	v_pk_mul_f32 v[4:5], v[4:5], v[34:35] op_sel_hi:[1,0]
	v_cvt_pk_bf16_f32 v2, v2, v3
	v_pk_add_f32 v[40:41], v[40:41], 1.0 op_sel_hi:[1,0]
	s_nop 0
	v_div_scale_f32 v43, s[4:5], v41, v41, v42
	v_rcp_f32_e32 v44, v43
	s_nop 0
	v_fma_f32 v45, -v43, v44, 1.0
	v_fmac_f32_e32 v44, v45, v44
	v_div_scale_f32 v45, vcc, v42, v41, v42
	v_mul_f32_e32 v46, v45, v44
	v_fma_f32 v47, -v43, v46, v45
	v_fmac_f32_e32 v46, v47, v44
	v_fma_f32 v43, -v43, v46, v45
	v_div_fmas_f32 v43, v43, v44, v46
	v_div_fixup_f32 v41, v43, v41, v42
	v_div_scale_f32 v42, s[4:5], v40, v40, v35
	v_rcp_f32_e32 v43, v42
	s_nop 0
	v_fma_f32 v44, -v42, v43, 1.0
	v_fmac_f32_e32 v43, v44, v43
	v_div_scale_f32 v44, vcc, v35, v40, v35
	v_mul_f32_e32 v45, v44, v43
	v_fma_f32 v46, -v42, v45, v44
	v_fmac_f32_e32 v45, v46, v43
	v_fma_f32 v42, -v42, v45, v44
	v_div_fmas_f32 v42, v42, v43, v45
	v_div_fixup_f32 v40, v42, v40, v35
	v_pk_mul_f32 v[4:5], v[4:5], v[40:41]
	s_nop 0
	v_cvt_pk_bf16_f32 v3, v4, v5
	global_store_dwordx2 v[38:39], v[2:3], off
	s_waitcnt vmcnt(7)
	v_mov_b32_e32 v2, v234
	v_mov_b32_e32 v3, v235
	v_lshlrev_b32_e32 v35, 16, v2
	v_and_b32_e32 v2, 0xffff0000, v2
	v_mul_f32_e32 v4, 0xbfb8aa3b, v35
	v_mul_f32_e32 v5, 0xbfb8aa3b, v2
	v_exp_f32_e32 v4, v4
	v_exp_f32_e32 v5, v5
	v_pk_mul_f32 v[6:7], v[6:7], v[34:35] op_sel_hi:[1,0]
	v_pk_add_f32 v[4:5], v[4:5], 1.0 op_sel_hi:[1,0]
	s_nop 0
	v_div_scale_f32 v40, s[4:5], v5, v5, v2
	v_rcp_f32_e32 v41, v40
	s_nop 0
	v_fma_f32 v42, -v40, v41, 1.0
	v_fmac_f32_e32 v41, v42, v41
	v_div_scale_f32 v42, vcc, v2, v5, v2
	v_mul_f32_e32 v43, v42, v41
	v_fma_f32 v44, -v40, v43, v42
	v_fmac_f32_e32 v43, v44, v41
	v_fma_f32 v40, -v40, v43, v42
	v_div_fmas_f32 v40, v40, v41, v43
	v_div_fixup_f32 v5, v40, v5, v2
	v_div_scale_f32 v2, s[4:5], v4, v4, v35
	v_rcp_f32_e32 v40, v2
	s_nop 0
	v_fma_f32 v41, -v2, v40, 1.0
	v_fmac_f32_e32 v40, v41, v40
	v_div_scale_f32 v41, vcc, v35, v4, v35
	v_mul_f32_e32 v42, v41, v40
	v_fma_f32 v43, -v2, v42, v41
	v_fmac_f32_e32 v42, v43, v40
	v_fma_f32 v2, -v2, v42, v41
	v_div_fmas_f32 v2, v2, v40, v42
	v_div_fixup_f32 v4, v2, v4, v35
	v_lshlrev_b32_e32 v35, 16, v3
	v_and_b32_e32 v40, 0xffff0000, v3
	v_mul_f32_e32 v2, 0xbfb8aa3b, v35
	v_mul_f32_e32 v3, 0xbfb8aa3b, v40
	v_exp_f32_e32 v2, v2
	v_exp_f32_e32 v3, v3
	v_pk_mul_f32 v[4:5], v[6:7], v[4:5]
	v_pk_mul_f32 v[6:7], v[8:9], v[34:35] op_sel_hi:[1,0]
	v_cvt_pk_bf16_f32 v4, v4, v5
	v_pk_add_f32 v[2:3], v[2:3], 1.0 op_sel_hi:[1,0]
	s_nop 0
	v_div_scale_f32 v8, s[4:5], v3, v3, v40
	v_rcp_f32_e32 v9, v8
	s_nop 0
	v_fma_f32 v41, -v8, v9, 1.0
	v_fmac_f32_e32 v9, v41, v9
	v_div_scale_f32 v41, vcc, v40, v3, v40
	v_mul_f32_e32 v42, v41, v9
	v_fma_f32 v43, -v8, v42, v41
	v_fmac_f32_e32 v42, v43, v9
	v_fma_f32 v8, -v8, v42, v41
	v_div_fmas_f32 v8, v8, v9, v42
	v_div_fixup_f32 v3, v8, v3, v40
	v_div_scale_f32 v8, s[4:5], v2, v2, v35
	v_rcp_f32_e32 v9, v8
	s_nop 0
	v_fma_f32 v40, -v8, v9, 1.0
	v_fmac_f32_e32 v9, v40, v9
	v_div_scale_f32 v40, vcc, v35, v2, v35
	v_mul_f32_e32 v41, v40, v9
	v_fma_f32 v42, -v8, v41, v40
	v_fmac_f32_e32 v41, v42, v9
	v_fma_f32 v8, -v8, v41, v40
	v_div_fmas_f32 v8, v8, v9, v41
	v_div_fixup_f32 v2, v8, v2, v35
	v_pk_mul_f32 v[2:3], v[6:7], v[2:3]
	v_pk_mul_f32 v[6:7], v[10:11], v[34:35] op_sel_hi:[1,0]
	v_cvt_pk_bf16_f32 v5, v2, v3
	s_waitcnt vmcnt(6)
; DI unsigned pack2(float a, float b) { f32x2 v = {a, b}; bf16x2_t r = __builtin_convertvector(v, bf16x2_t); return __builtin_bit_cast(unsigned, r); }
; DI float bflo(unsigned v) { return __uint_as_float(v << 16); }
; DI float bfhi(unsigned v) { return __uint_as_float(v & 0xffff0000u); }
; DI int otid() { int t = threadIdx.x; asm volatile("" : "+v"(t)); return t; }
; DI size_t blk(size_t row, int k, int R) { return ((size_t)(k >> 5) * R + row) * 32 + (k & 31); }
; DI float silu_f(float x) { return x / (1.f + __expf(-x)); }
; DI void store_gated(const f32x16 (&o)[2], float inv, bf16_t* G, size_t tok, int head) {
;   const int h = (otid() & 63) >> 5;
; #pragma unroll
;   for (int dt = 0; dt < 2; ++dt)
; #pragma unroll
;     for (int g = 0; g < 4; ++g) {
;       bf16_t* q = G + blk(tok, head * 64 + 32 * dt + 8 * g + 4 * h, NTOK);
;       const u32x2 gv = *(const u32x2*)q;
;       const float a0 = o[dt][4 * g] * inv * silu_f(bflo(gv[0])), a1 = o[dt][4 * g + 1] * inv * silu_f(bfhi(gv[0]));
;       const float a2 = o[dt][4 * g + 2] * inv * silu_f(bflo(gv[1])), a3 = o[dt][4 * g + 3] * inv * silu_f(bfhi(gv[1]));
;       *(u32x2*)q = (u32x2){pack2(a0, a1), pack2(a2, a3)};
;     }
; }
	v_mov_b32_e32 v2, v236
	v_mov_b32_e32 v3, v237
	v_lshlrev_b32_e32 v8, 16, v2
	v_and_b32_e32 v2, 0xffff0000, v2
	global_store_dwordx2 v[38:39], v[4:5], off offset:16
	v_mul_f32_e32 v4, 0xbfb8aa3b, v8
	v_mul_f32_e32 v5, 0xbfb8aa3b, v2
	v_exp_f32_e32 v4, v4
	v_exp_f32_e32 v5, v5
	s_nop 0
	v_pk_add_f32 v[4:5], v[4:5], 1.0 op_sel_hi:[1,0]
	s_nop 0
	v_div_scale_f32 v9, s[4:5], v5, v5, v2
	v_rcp_f32_e32 v10, v9
	s_nop 0
	v_fma_f32 v11, -v9, v10, 1.0
	v_fmac_f32_e32 v10, v11, v10
	v_div_scale_f32 v11, vcc, v2, v5, v2
	v_mul_f32_e32 v35, v11, v10
	v_fma_f32 v40, -v9, v35, v11
	v_fmac_f32_e32 v35, v40, v10
	v_fma_f32 v9, -v9, v35, v11
	v_div_fmas_f32 v9, v9, v10, v35
	v_div_fixup_f32 v5, v9, v5, v2
	v_div_scale_f32 v2, s[4:5], v4, v4, v8
	v_rcp_f32_e32 v9, v2
	s_nop 0
	v_fma_f32 v10, -v2, v9, 1.0
	v_fmac_f32_e32 v9, v10, v9
	v_div_scale_f32 v10, vcc, v8, v4, v8
	v_mul_f32_e32 v11, v10, v9
	v_fma_f32 v35, -v2, v11, v10
	v_fmac_f32_e32 v11, v35, v9
	v_fma_f32 v2, -v2, v11, v10
	v_div_fmas_f32 v2, v2, v9, v11
	v_div_fixup_f32 v4, v2, v4, v8
	v_lshlrev_b32_e32 v8, 16, v3
	v_and_b32_e32 v9, 0xffff0000, v3
	v_mul_f32_e32 v2, 0xbfb8aa3b, v8
	v_mul_f32_e32 v3, 0xbfb8aa3b, v9
	v_exp_f32_e32 v2, v2
	v_exp_f32_e32 v3, v3
	v_pk_mul_f32 v[4:5], v[6:7], v[4:5]
	v_pk_mul_f32 v[6:7], v[12:13], v[34:35] op_sel_hi:[1,0]
	v_cvt_pk_bf16_f32 v4, v4, v5
	v_pk_add_f32 v[2:3], v[2:3], 1.0 op_sel_hi:[1,0]
	s_nop 0
	v_div_scale_f32 v10, s[4:5], v3, v3, v9
	v_rcp_f32_e32 v11, v10
	s_nop 0
	v_fma_f32 v12, -v10, v11, 1.0
	v_fmac_f32_e32 v11, v12, v11
	v_div_scale_f32 v12, vcc, v9, v3, v9
	v_mul_f32_e32 v13, v12, v11
	v_fma_f32 v35, -v10, v13, v12
	v_fmac_f32_e32 v13, v35, v11
	v_fma_f32 v10, -v10, v13, v12
	v_div_fmas_f32 v10, v10, v11, v13
	v_div_fixup_f32 v3, v10, v3, v9
	v_div_scale_f32 v9, s[4:5], v2, v2, v8
	v_rcp_f32_e32 v10, v9
	s_nop 0
	v_fma_f32 v11, -v9, v10, 1.0
	v_fmac_f32_e32 v10, v11, v10
	v_div_scale_f32 v11, vcc, v8, v2, v8
	v_mul_f32_e32 v12, v11, v10
	v_fma_f32 v13, -v9, v12, v11
	v_fmac_f32_e32 v12, v13, v10
	v_fma_f32 v9, -v9, v12, v11
	v_div_fmas_f32 v9, v9, v10, v12
	v_div_fixup_f32 v2, v9, v2, v8
	v_pk_mul_f32 v[2:3], v[6:7], v[2:3]
	v_pk_mul_f32 v[6:7], v[14:15], v[34:35] op_sel_hi:[1,0]
	v_cvt_pk_bf16_f32 v5, v2, v3
	s_waitcnt vmcnt(6)
	v_mov_b32_e32 v2, v238
	v_mov_b32_e32 v3, v239
	v_lshlrev_b32_e32 v8, 16, v2
	v_and_b32_e32 v2, 0xffff0000, v2
	global_store_dwordx2 v[38:39], v[4:5], off offset:32
	v_mul_f32_e32 v4, 0xbfb8aa3b, v8
	v_mul_f32_e32 v5, 0xbfb8aa3b, v2
	v_exp_f32_e32 v4, v4
	v_exp_f32_e32 v5, v5
	s_nop 0
	v_pk_add_f32 v[4:5], v[4:5], 1.0 op_sel_hi:[1,0]
	s_nop 0
	v_div_scale_f32 v9, s[4:5], v5, v5, v2
	v_rcp_f32_e32 v10, v9
	s_nop 0
	v_fma_f32 v11, -v9, v10, 1.0
	v_fmac_f32_e32 v10, v11, v10
	v_div_scale_f32 v11, vcc, v2, v5, v2
	v_mul_f32_e32 v12, v11, v10
	v_fma_f32 v13, -v9, v12, v11
	v_fmac_f32_e32 v12, v13, v10
	v_fma_f32 v9, -v9, v12, v11
	v_div_fmas_f32 v9, v9, v10, v12
	v_div_fixup_f32 v5, v9, v5, v2
	v_div_scale_f32 v2, s[4:5], v4, v4, v8
	v_rcp_f32_e32 v9, v2
	s_nop 0
	v_fma_f32 v10, -v2, v9, 1.0
	v_fmac_f32_e32 v9, v10, v9
	v_div_scale_f32 v10, vcc, v8, v4, v8
	v_mul_f32_e32 v11, v10, v9
	v_fma_f32 v12, -v2, v11, v10
	v_fmac_f32_e32 v11, v12, v9
	v_fma_f32 v2, -v2, v11, v10
	v_div_fmas_f32 v2, v2, v9, v11
	v_div_fixup_f32 v4, v2, v4, v8
	v_lshlrev_b32_e32 v8, 16, v3
	v_and_b32_e32 v9, 0xffff0000, v3
	v_mul_f32_e32 v2, 0xbfb8aa3b, v8
	v_mul_f32_e32 v3, 0xbfb8aa3b, v9
	v_exp_f32_e32 v2, v2
	v_exp_f32_e32 v3, v3
	v_pk_mul_f32 v[4:5], v[6:7], v[4:5]
	v_pk_mul_f32 v[6:7], v[16:17], v[34:35] op_sel_hi:[1,0]
	v_cvt_pk_bf16_f32 v4, v4, v5
	v_pk_add_f32 v[2:3], v[2:3], 1.0 op_sel_hi:[1,0]
	s_nop 0
	v_div_scale_f32 v10, s[4:5], v3, v3, v9
	v_rcp_f32_e32 v11, v10
	s_nop 0
	v_fma_f32 v12, -v10, v11, 1.0
	v_fmac_f32_e32 v11, v12, v11
	v_div_scale_f32 v12, vcc, v9, v3, v9
	v_mul_f32_e32 v13, v12, v11
	v_fma_f32 v14, -v10, v13, v12
	v_fmac_f32_e32 v13, v14, v11
	v_fma_f32 v10, -v10, v13, v12
	v_div_fmas_f32 v10, v10, v11, v13
	v_div_fixup_f32 v3, v10, v3, v9
	v_div_scale_f32 v9, s[4:5], v2, v2, v8
	v_rcp_f32_e32 v10, v9
	s_nop 0
	v_fma_f32 v11, -v9, v10, 1.0
	v_fmac_f32_e32 v10, v11, v10
	v_div_scale_f32 v11, vcc, v8, v2, v8
	v_mul_f32_e32 v12, v11, v10
	v_fma_f32 v13, -v9, v12, v11
	v_fmac_f32_e32 v12, v13, v10
	v_fma_f32 v9, -v9, v12, v11
	v_div_fmas_f32 v9, v9, v10, v12
	v_div_fixup_f32 v2, v9, v2, v8
	v_pk_mul_f32 v[2:3], v[6:7], v[2:3]
	v_pk_mul_f32 v[8:9], v[18:19], v[34:35] op_sel_hi:[1,0]
	v_cvt_pk_bf16_f32 v5, v2, v3
	v_lshl_add_u64 v[2:3], v[36:37], 0, s[2:3]
	v_lshl_add_u64 v[2:3], v[2:3], 0, v[0:1]
	global_store_dwordx2 v[38:39], v[4:5], off offset:48
	s_waitcnt vmcnt(7)
; DI unsigned pack2(float a, float b) { f32x2 v = {a, b}; bf16x2_t r = __builtin_convertvector(v, bf16x2_t); return __builtin_bit_cast(unsigned, r); }
; DI float bflo(unsigned v) { return __uint_as_float(v << 16); }
; DI float bfhi(unsigned v) { return __uint_as_float(v & 0xffff0000u); }
; DI int otid() { int t = threadIdx.x; asm volatile("" : "+v"(t)); return t; }
; DI size_t blk(size_t row, int k, int R) { return ((size_t)(k >> 5) * R + row) * 32 + (k & 31); }
; DI float silu_f(float x) { return x / (1.f + __expf(-x)); }
; DI void store_gated(const f32x16 (&o)[2], float inv, bf16_t* G, size_t tok, int head) {
;   const int h = (otid() & 63) >> 5;
; #pragma unroll
;   for (int dt = 0; dt < 2; ++dt)
; #pragma unroll
;     for (int g = 0; g < 4; ++g) {
;       bf16_t* q = G + blk(tok, head * 64 + 32 * dt + 8 * g + 4 * h, NTOK);
;       const u32x2 gv = *(const u32x2*)q;
;       const float a0 = o[dt][4 * g] * inv * silu_f(bflo(gv[0])), a1 = o[dt][4 * g + 1] * inv * silu_f(bfhi(gv[0]));
;       const float a2 = o[dt][4 * g + 2] * inv * silu_f(bflo(gv[1])), a3 = o[dt][4 * g + 3] * inv * silu_f(bfhi(gv[1]));
;       *(u32x2*)q = (u32x2){pack2(a0, a1), pack2(a2, a3)};
;     }
; }
	v_mov_b32_e32 v4, v240
	v_mov_b32_e32 v5, v241
	v_lshlrev_b32_e32 v0, 16, v4
	v_and_b32_e32 v4, 0xffff0000, v4
	v_mul_f32_e32 v6, 0xbfb8aa3b, v0
	v_mul_f32_e32 v7, 0xbfb8aa3b, v4
	v_exp_f32_e32 v6, v6
	v_exp_f32_e32 v7, v7
	s_nop 0
	v_pk_add_f32 v[6:7], v[6:7], 1.0 op_sel_hi:[1,0]
	s_nop 0
	v_div_scale_f32 v10, s[2:3], v7, v7, v4
	v_rcp_f32_e32 v11, v10
	s_nop 0
	v_fma_f32 v12, -v10, v11, 1.0
	v_fmac_f32_e32 v11, v12, v11
	v_div_scale_f32 v12, vcc, v4, v7, v4
	v_mul_f32_e32 v13, v12, v11
	v_fma_f32 v14, -v10, v13, v12
	v_fmac_f32_e32 v13, v14, v11
	v_fma_f32 v10, -v10, v13, v12
	v_div_fmas_f32 v10, v10, v11, v13
	v_div_fixup_f32 v7, v10, v7, v4
	v_div_scale_f32 v4, s[2:3], v6, v6, v0
	v_rcp_f32_e32 v10, v4
	s_nop 0
	v_fma_f32 v11, -v4, v10, 1.0
	v_fmac_f32_e32 v10, v11, v10
	v_div_scale_f32 v11, vcc, v0, v6, v0
	v_mul_f32_e32 v12, v11, v10
	v_fma_f32 v13, -v4, v12, v11
	v_fmac_f32_e32 v12, v13, v10
	v_fma_f32 v4, -v4, v12, v11
	v_div_fmas_f32 v4, v4, v10, v12
	v_div_fixup_f32 v6, v4, v6, v0
	v_lshlrev_b32_e32 v0, 16, v5
	v_and_b32_e32 v10, 0xffff0000, v5
	v_mul_f32_e32 v4, 0xbfb8aa3b, v0
	v_mul_f32_e32 v5, 0xbfb8aa3b, v10
	v_exp_f32_e32 v4, v4
	v_exp_f32_e32 v5, v5
	v_pk_mul_f32 v[6:7], v[8:9], v[6:7]
	v_pk_mul_f32 v[8:9], v[20:21], v[34:35] op_sel_hi:[1,0]
	v_cvt_pk_bf16_f32 v6, v6, v7
	v_pk_add_f32 v[4:5], v[4:5], 1.0 op_sel_hi:[1,0]
	s_nop 0
	v_div_scale_f32 v11, s[2:3], v5, v5, v10
	v_rcp_f32_e32 v12, v11
	s_nop 0
	v_fma_f32 v13, -v11, v12, 1.0
	v_fmac_f32_e32 v12, v13, v12
	v_div_scale_f32 v13, vcc, v10, v5, v10
	v_mul_f32_e32 v14, v13, v12
	v_fma_f32 v15, -v11, v14, v13
	v_fmac_f32_e32 v14, v15, v12
	v_fma_f32 v11, -v11, v14, v13
	v_div_fmas_f32 v11, v11, v12, v14
	v_div_fixup_f32 v5, v11, v5, v10
	v_div_scale_f32 v10, s[2:3], v4, v4, v0
	v_rcp_f32_e32 v11, v10
	s_nop 0
	v_fma_f32 v12, -v10, v11, 1.0
	v_fmac_f32_e32 v11, v12, v11
	v_div_scale_f32 v12, vcc, v0, v4, v0
	v_mul_f32_e32 v13, v12, v11
	v_fma_f32 v14, -v10, v13, v12
	v_fmac_f32_e32 v13, v14, v11
	v_fma_f32 v10, -v10, v13, v12
	v_div_fmas_f32 v10, v10, v11, v13
	v_div_fixup_f32 v4, v10, v4, v0
	v_pk_mul_f32 v[4:5], v[8:9], v[4:5]
	v_pk_mul_f32 v[8:9], v[22:23], v[34:35] op_sel_hi:[1,0]
	v_cvt_pk_bf16_f32 v7, v4, v5
	s_waitcnt vmcnt(6)
	v_mov_b32_e32 v4, v242
	v_mov_b32_e32 v5, v243
	v_lshlrev_b32_e32 v0, 16, v4
	v_and_b32_e32 v4, 0xffff0000, v4
	global_store_dwordx2 v[2:3], v[6:7], off
	v_mul_f32_e32 v6, 0xbfb8aa3b, v0
	v_mul_f32_e32 v7, 0xbfb8aa3b, v4
	v_exp_f32_e32 v6, v6
	v_exp_f32_e32 v7, v7
	s_nop 0
	v_pk_add_f32 v[6:7], v[6:7], 1.0 op_sel_hi:[1,0]
	s_nop 0
	v_div_scale_f32 v10, s[2:3], v7, v7, v4
	v_rcp_f32_e32 v11, v10
	s_nop 0
	v_fma_f32 v12, -v10, v11, 1.0
	v_fmac_f32_e32 v11, v12, v11
	v_div_scale_f32 v12, vcc, v4, v7, v4
	v_mul_f32_e32 v13, v12, v11
	v_fma_f32 v14, -v10, v13, v12
	v_fmac_f32_e32 v13, v14, v11
	v_fma_f32 v10, -v10, v13, v12
	v_div_fmas_f32 v10, v10, v11, v13
	v_div_fixup_f32 v7, v10, v7, v4
	v_div_scale_f32 v4, s[2:3], v6, v6, v0
	v_rcp_f32_e32 v10, v4
	s_nop 0
	v_fma_f32 v11, -v4, v10, 1.0
	v_fmac_f32_e32 v10, v11, v10
	v_div_scale_f32 v11, vcc, v0, v6, v0
	v_mul_f32_e32 v12, v11, v10
	v_fma_f32 v13, -v4, v12, v11
	v_fmac_f32_e32 v12, v13, v10
	v_fma_f32 v4, -v4, v12, v11
	v_div_fmas_f32 v4, v4, v10, v12
	v_div_fixup_f32 v6, v4, v6, v0
	v_lshlrev_b32_e32 v0, 16, v5
	v_and_b32_e32 v10, 0xffff0000, v5
	v_mul_f32_e32 v4, 0xbfb8aa3b, v0
	v_mul_f32_e32 v5, 0xbfb8aa3b, v10
	v_exp_f32_e32 v4, v4
	v_exp_f32_e32 v5, v5
	v_pk_mul_f32 v[6:7], v[8:9], v[6:7]
	v_pk_mul_f32 v[8:9], v[24:25], v[34:35] op_sel_hi:[1,0]
	v_cvt_pk_bf16_f32 v6, v6, v7
	v_pk_add_f32 v[4:5], v[4:5], 1.0 op_sel_hi:[1,0]
	s_nop 0
	v_div_scale_f32 v11, s[2:3], v5, v5, v10
	v_rcp_f32_e32 v12, v11
	s_nop 0
	v_fma_f32 v13, -v11, v12, 1.0
	v_fmac_f32_e32 v12, v13, v12
	v_div_scale_f32 v13, vcc, v10, v5, v10
	v_mul_f32_e32 v14, v13, v12
	v_fma_f32 v15, -v11, v14, v13
	v_fmac_f32_e32 v14, v15, v12
	v_fma_f32 v11, -v11, v14, v13
	v_div_fmas_f32 v11, v11, v12, v14
	v_div_fixup_f32 v5, v11, v5, v10
	v_div_scale_f32 v10, s[2:3], v4, v4, v0
	v_rcp_f32_e32 v11, v10
	s_nop 0
	v_fma_f32 v12, -v10, v11, 1.0
	v_fmac_f32_e32 v11, v12, v11
	v_div_scale_f32 v12, vcc, v0, v4, v0
	v_mul_f32_e32 v13, v12, v11
	v_fma_f32 v14, -v10, v13, v12
	v_fmac_f32_e32 v13, v14, v11
	v_fma_f32 v10, -v10, v13, v12
	v_div_fmas_f32 v10, v10, v11, v13
	v_div_fixup_f32 v4, v10, v4, v0
	v_pk_mul_f32 v[4:5], v[8:9], v[4:5]
	v_pk_mul_f32 v[8:9], v[26:27], v[34:35] op_sel_hi:[1,0]
	v_cvt_pk_bf16_f32 v7, v4, v5
	s_waitcnt vmcnt(6)
; DI unsigned pack2(float a, float b) { f32x2 v = {a, b}; bf16x2_t r = __builtin_convertvector(v, bf16x2_t); return __builtin_bit_cast(unsigned, r); }
; DI float bflo(unsigned v) { return __uint_as_float(v << 16); }
; DI float bfhi(unsigned v) { return __uint_as_float(v & 0xffff0000u); }
; DI int otid() { int t = threadIdx.x; asm volatile("" : "+v"(t)); return t; }
; DI size_t blk(size_t row, int k, int R) { return ((size_t)(k >> 5) * R + row) * 32 + (k & 31); }
; DI float silu_f(float x) { return x / (1.f + __expf(-x)); }
; DI void store_gated(const f32x16 (&o)[2], float inv, bf16_t* G, size_t tok, int head) {
;   const int h = (otid() & 63) >> 5;
; #pragma unroll
;   for (int dt = 0; dt < 2; ++dt)
; #pragma unroll
;     for (int g = 0; g < 4; ++g) {
;       bf16_t* q = G + blk(tok, head * 64 + 32 * dt + 8 * g + 4 * h, NTOK);
;       const u32x2 gv = *(const u32x2*)q;
;       const float a0 = o[dt][4 * g] * inv * silu_f(bflo(gv[0])), a1 = o[dt][4 * g + 1] * inv * silu_f(bfhi(gv[0]));
;       const float a2 = o[dt][4 * g + 2] * inv * silu_f(bflo(gv[1])), a3 = o[dt][4 * g + 3] * inv * silu_f(bfhi(gv[1]));
;       *(u32x2*)q = (u32x2){pack2(a0, a1), pack2(a2, a3)};
;     }
; }
; DI void fox_unit(const Params& p, int u, char* smem, bool probe = false) {
;     ...
;   store_gated(o, 1.f / l, p.G, tok, hd);
; }
	v_mov_b32_e32 v4, v244
	v_mov_b32_e32 v5, v245
	v_lshlrev_b32_e32 v0, 16, v4
	v_and_b32_e32 v4, 0xffff0000, v4
	global_store_dwordx2 v[2:3], v[6:7], off offset:16
	v_mul_f32_e32 v6, 0xbfb8aa3b, v0
	v_mul_f32_e32 v7, 0xbfb8aa3b, v4
	v_exp_f32_e32 v6, v6
	v_exp_f32_e32 v7, v7
	s_nop 0
	v_pk_add_f32 v[6:7], v[6:7], 1.0 op_sel_hi:[1,0]
	s_nop 0
	v_div_scale_f32 v10, s[2:3], v7, v7, v4
	v_rcp_f32_e32 v11, v10
	s_nop 0
	v_fma_f32 v12, -v10, v11, 1.0
	v_fmac_f32_e32 v11, v12, v11
	v_div_scale_f32 v12, vcc, v4, v7, v4
	v_mul_f32_e32 v13, v12, v11
	v_fma_f32 v14, -v10, v13, v12
	v_fmac_f32_e32 v13, v14, v11
	v_fma_f32 v10, -v10, v13, v12
	v_div_fmas_f32 v10, v10, v11, v13
	v_div_fixup_f32 v7, v10, v7, v4
	v_div_scale_f32 v4, s[2:3], v6, v6, v0
	v_rcp_f32_e32 v10, v4
	s_nop 0
	v_fma_f32 v11, -v4, v10, 1.0
	v_fmac_f32_e32 v10, v11, v10
	v_div_scale_f32 v11, vcc, v0, v6, v0
	v_mul_f32_e32 v12, v11, v10
	v_fma_f32 v13, -v4, v12, v11
	v_fmac_f32_e32 v12, v13, v10
	v_fma_f32 v4, -v4, v12, v11
	v_div_fmas_f32 v4, v4, v10, v12
	v_div_fixup_f32 v6, v4, v6, v0
	v_lshlrev_b32_e32 v0, 16, v5
	v_and_b32_e32 v10, 0xffff0000, v5
	v_mul_f32_e32 v4, 0xbfb8aa3b, v0
	v_mul_f32_e32 v5, 0xbfb8aa3b, v10
	v_exp_f32_e32 v4, v4
	v_exp_f32_e32 v5, v5
	v_pk_mul_f32 v[6:7], v[8:9], v[6:7]
	v_pk_mul_f32 v[8:9], v[28:29], v[34:35] op_sel_hi:[1,0]
	v_cvt_pk_bf16_f32 v6, v6, v7
	v_pk_add_f32 v[4:5], v[4:5], 1.0 op_sel_hi:[1,0]
	s_nop 0
	v_div_scale_f32 v11, s[2:3], v5, v5, v10
	v_rcp_f32_e32 v12, v11
	s_nop 0
	v_fma_f32 v13, -v11, v12, 1.0
	v_fmac_f32_e32 v12, v13, v12
	v_div_scale_f32 v13, vcc, v10, v5, v10
	v_mul_f32_e32 v14, v13, v12
	v_fma_f32 v15, -v11, v14, v13
	v_fmac_f32_e32 v14, v15, v12
	v_fma_f32 v11, -v11, v14, v13
	v_div_fmas_f32 v11, v11, v12, v14
	v_div_fixup_f32 v5, v11, v5, v10
	v_div_scale_f32 v10, s[2:3], v4, v4, v0
	v_rcp_f32_e32 v11, v10
	s_nop 0
	v_fma_f32 v12, -v10, v11, 1.0
	v_fmac_f32_e32 v11, v12, v11
	v_div_scale_f32 v12, vcc, v0, v4, v0
	v_mul_f32_e32 v13, v12, v11
	v_fma_f32 v14, -v10, v13, v12
	v_fmac_f32_e32 v13, v14, v11
	v_fma_f32 v10, -v10, v13, v12
	v_div_fmas_f32 v10, v10, v11, v13
	v_div_fixup_f32 v4, v10, v4, v0
	v_pk_mul_f32 v[4:5], v[8:9], v[4:5]
	v_pk_mul_f32 v[8:9], v[30:31], v[34:35] op_sel_hi:[1,0]
	v_cvt_pk_bf16_f32 v7, v4, v5
	s_waitcnt vmcnt(6)
	v_mov_b32_e32 v4, v246
	v_mov_b32_e32 v5, v247
	v_lshlrev_b32_e32 v0, 16, v4
	v_and_b32_e32 v4, 0xffff0000, v4
	global_store_dwordx2 v[2:3], v[6:7], off offset:32
	v_mul_f32_e32 v6, 0xbfb8aa3b, v0
	v_mul_f32_e32 v7, 0xbfb8aa3b, v4
	v_exp_f32_e32 v6, v6
	v_exp_f32_e32 v7, v7
	s_nop 0
	v_pk_add_f32 v[6:7], v[6:7], 1.0 op_sel_hi:[1,0]
	s_nop 0
	v_div_scale_f32 v10, s[2:3], v7, v7, v4
	v_rcp_f32_e32 v11, v10
	s_nop 0
	v_fma_f32 v12, -v10, v11, 1.0
	v_fmac_f32_e32 v11, v12, v11
	v_div_scale_f32 v12, vcc, v4, v7, v4
	v_mul_f32_e32 v13, v12, v11
	v_fma_f32 v14, -v10, v13, v12
	v_fmac_f32_e32 v13, v14, v11
	v_fma_f32 v10, -v10, v13, v12
	v_div_fmas_f32 v10, v10, v11, v13
	v_div_fixup_f32 v7, v10, v7, v4
	v_div_scale_f32 v4, s[2:3], v6, v6, v0
	v_rcp_f32_e32 v10, v4
	s_nop 0
	v_fma_f32 v11, -v4, v10, 1.0
	v_fmac_f32_e32 v10, v11, v10
	v_div_scale_f32 v11, vcc, v0, v6, v0
	v_mul_f32_e32 v12, v11, v10
	v_fma_f32 v13, -v4, v12, v11
	v_fmac_f32_e32 v12, v13, v10
	v_fma_f32 v4, -v4, v12, v11
	v_div_fmas_f32 v4, v4, v10, v12
	v_div_fixup_f32 v6, v4, v6, v0
	v_lshlrev_b32_e32 v0, 16, v5
	v_and_b32_e32 v10, 0xffff0000, v5
	v_mul_f32_e32 v4, 0xbfb8aa3b, v0
	v_mul_f32_e32 v5, 0xbfb8aa3b, v10
	v_exp_f32_e32 v4, v4
	v_exp_f32_e32 v5, v5
	v_pk_mul_f32 v[6:7], v[8:9], v[6:7]
	v_pk_mul_f32 v[8:9], v[32:33], v[34:35] op_sel_hi:[1,0]
	v_cvt_pk_bf16_f32 v6, v6, v7
	v_pk_add_f32 v[4:5], v[4:5], 1.0 op_sel_hi:[1,0]
	s_nop 0
	v_div_scale_f32 v11, s[2:3], v5, v5, v10
	v_rcp_f32_e32 v12, v11
	s_nop 0
	v_fma_f32 v13, -v11, v12, 1.0
	v_fmac_f32_e32 v12, v13, v12
	v_div_scale_f32 v13, vcc, v10, v5, v10
	v_mul_f32_e32 v14, v13, v12
	v_fma_f32 v15, -v11, v14, v13
	v_fmac_f32_e32 v14, v15, v12
	v_fma_f32 v11, -v11, v14, v13
	v_div_fmas_f32 v11, v11, v12, v14
	v_div_fixup_f32 v5, v11, v5, v10
	v_div_scale_f32 v10, s[2:3], v4, v4, v0
	v_rcp_f32_e32 v11, v10
	s_nop 0
	v_fma_f32 v12, -v10, v11, 1.0
	v_fmac_f32_e32 v11, v12, v11
	v_div_scale_f32 v12, vcc, v0, v4, v0
	v_mul_f32_e32 v13, v12, v11
	v_fma_f32 v14, -v10, v13, v12
	v_fmac_f32_e32 v13, v14, v11
	v_fma_f32 v10, -v10, v13, v12
	v_div_fmas_f32 v10, v10, v11, v13
	v_div_fixup_f32 v4, v10, v4, v0
	v_pk_mul_f32 v[4:5], v[8:9], v[4:5]
	s_nop 0
	v_cvt_pk_bf16_f32 v7, v4, v5
	global_store_dwordx2 v[2:3], v[6:7], off offset:48
	s_cbranch_scc1 .LBB0_870

; __global__ void __launch_bounds__(256, 2) mega_kernel(Params p) {
	.amdhsa_kernel _Z11mega_kernel6Params
		.amdhsa_group_segment_fixed_size 0
		.amdhsa_private_segment_fixed_size 0
		.amdhsa_kernarg_size 2784
		.amdhsa_user_sgpr_count 2
		.amdhsa_user_sgpr_dispatch_ptr 0
		.amdhsa_user_sgpr_queue_ptr 0
		.amdhsa_user_sgpr_kernarg_segment_ptr 1
		.amdhsa_user_sgpr_dispatch_id 0
		.amdhsa_user_sgpr_kernarg_preload_length 0
		.amdhsa_user_sgpr_kernarg_preload_offset 0
		.amdhsa_user_sgpr_private_segment_size 0
		.amdhsa_uses_dynamic_stack 0
		.amdhsa_enable_private_segment 0
		.amdhsa_system_sgpr_workgroup_id_x 1
		.amdhsa_system_sgpr_workgroup_id_y 0
		.amdhsa_system_sgpr_workgroup_id_z 0
		.amdhsa_system_sgpr_workgroup_info 0
		.amdhsa_system_vgpr_workitem_id 2
		.amdhsa_next_free_vgpr 252
		.amdhsa_next_free_sgpr 102
		.amdhsa_accum_offset 252
		.amdhsa_reserve_vcc 1
		.amdhsa_float_round_mode_32 0
		.amdhsa_float_round_mode_16_64 0
		.amdhsa_float_denorm_mode_32 3
		.amdhsa_float_denorm_mode_16_64 3
		.amdhsa_dx10_clamp 1
		.amdhsa_ieee_mode 1
		.amdhsa_fp16_overflow 0
		.amdhsa_tg_split 0
		.amdhsa_exception_fp_ieee_invalid_op 0
		.amdhsa_exception_fp_denorm_src 0
		.amdhsa_exception_fp_ieee_div_zero 0
		.amdhsa_exception_fp_ieee_overflow 0
		.amdhsa_exception_fp_ieee_underflow 0
		.amdhsa_exception_fp_ieee_inexact 0
		.amdhsa_exception_int_div_zero 0
	.end_amdhsa_kernel

; __global__ void __launch_bounds__(256, 2) mega_kernel(Params p) {
amdhsa.kernels:
  - .agpr_count:     0
    .args:
      - .offset:         0
        .size:           2528
        .value_kind:     by_value
      - .offset:         2528
        .size:           4
        .value_kind:     hidden_block_count_x
      - .offset:         2532
        .size:           4
        .value_kind:     hidden_block_count_y
      - .offset:         2536
        .size:           4
        .value_kind:     hidden_block_count_z
      - .offset:         2540
        .size:           2
        .value_kind:     hidden_group_size_x
      - .offset:         2542
        .size:           2
        .value_kind:     hidden_group_size_y
      - .offset:         2544
        .size:           2
        .value_kind:     hidden_group_size_z
      - .offset:         2546
        .size:           2
        .value_kind:     hidden_remainder_x
      - .offset:         2548
        .size:           2
        .value_kind:     hidden_remainder_y
      - .offset:         2550
        .size:           2
        .value_kind:     hidden_remainder_z
      - .offset:         2568
        .size:           8
        .value_kind:     hidden_global_offset_x
      - .offset:         2576
        .size:           8
        .value_kind:     hidden_global_offset_y
      - .offset:         2584
        .size:           8
        .value_kind:     hidden_global_offset_z
      - .offset:         2592
        .size:           2
        .value_kind:     hidden_grid_dims
      - .offset:         2616
        .size:           8
        .value_kind:     hidden_multigrid_sync_arg
      - .offset:         2648
        .size:           4
        .value_kind:     hidden_dynamic_lds_size
    .group_segment_fixed_size: 0
    .kernarg_segment_align: 8
    .kernarg_segment_size: 2784
    .language:       OpenCL C
    .language_version:
      - 2
      - 0
    .max_flat_workgroup_size: 256
    .name:           _Z11mega_kernel6Params
    .private_segment_fixed_size: 0
    .sgpr_count:     108
    .sgpr_spill_count: 128
    .symbol:         _Z11mega_kernel6Params.kd
    .uniform_work_group_size: 1
    .uses_dynamic_stack: false
    .vgpr_count:     252
    .vgpr_spill_count: 0
    .wavefront_size: 64
